# phase 0 weight transposes (W_in, W_out, W_pq): one output row and eight consecutive k per thread -- coalesced column loads, one 16-byte store instead of four scattered 4-byte stores
# speedup vs baseline: 1.0157x; 1.0031x over previous
; DEVI uint32_t pk(float a, float b) { const hwf32x2 v = {a, b}; return __builtin_bit_cast(uint32_t, __builtin_convertvector(v, hwbf16x2)); }
; __device__ void phase_prep(const P& p, int vb, int nvb) {
;     ...
;     uint16_t* o = (uint16_t*)(ws + WS_WT_IN); const float* w = p.in[3]; const float* g = p.in[2];
;     for (size_t i = gid; i < (size_t)512 * 1440; i += gsz) {
;       const int k = 2 * (int)(i / 1440), n = (int)(i % 1440);
;       *(uint32_t*)(o + (size_t)n * 1024 + k) = pk(w[(size_t)k * 1440 + n] * g[k], w[(size_t)(k + 1) * 1440 + n] * g[k + 1]);
;     }
.LBB0_5:
	s_or_b64 exec, exec, s[4:5]
	s_load_dwordx16 s[60:75], s[0:1], 0x0
	s_ashr_i32 s3, s2, 31
	s_lshl_b64 s[4:5], s[2:3], 8
	v_mov_b32_e32 v2, v178
	v_writelane_b32 v248, s4, 2
	v_ashrrev_i32_e32 v3, 31, v2
	s_ashr_i32 s93, s82, 31
	s_mov_b32 s92, s82
	v_writelane_b32 v248, s5, 3
	v_lshl_add_u64 v[6:7], s[4:5], 0, v[2:3]
	s_mov_b64 s[4:5], 0xb4000
	s_lshl_b64 s[24:25], s[92:93], 8
	v_cmp_gt_u64_e32 vcc, s[4:5], v[6:7]
	s_and_saveexec_b64 s[4:5], vcc
	s_cbranch_execz .LBB0_8
	s_waitcnt lgkmcnt(0)
	s_mov_b32 s12, 0x5b05b06
	v_mov_b32_e32 v200, v6
	v_lshrrev_b32_e32 v201, 5, v200
	v_mul_hi_u32 v201, v201, s12
	v_mul_u32_u24_e32 v202, 0x5a0, v201
	v_sub_u32_e32 v202, v200, v202
	v_mul_u32_u24_e32 v203, 0xb400, v201
	v_lshl_add_u32 v203, v202, 2, v203
	v_lshlrev_b32_e32 v204, 5, v201
	v_lshlrev_b32_e32 v205, 4, v201
	v_lshl_or_b32 v205, v202, 11, v205
	v_add_u32_e32 v191, 0x1680, v203
	v_add_u32_e32 v192, 0x2d00, v203
	v_add_u32_e32 v193, 0x4380, v203
	v_add_u32_e32 v194, 0x5a00, v203
	v_add_u32_e32 v195, 0x7080, v203
	v_add_u32_e32 v196, 0x8700, v203
	v_add_u32_e32 v197, 0x9d80, v203
	global_load_dword v210, v203, s[66:67]
	global_load_dword v211, v191, s[66:67]
	global_load_dword v212, v192, s[66:67]
	global_load_dword v213, v193, s[66:67]
	global_load_dword v214, v194, s[66:67]
	global_load_dword v215, v195, s[66:67]
	global_load_dword v216, v196, s[66:67]
	global_load_dword v217, v197, s[66:67]
	global_load_dwordx4 v[218:221], v204, s[64:65]
	global_load_dwordx4 v[222:225], v204, s[64:65] offset:16
	s_mov_b32 s13, 0xd000
	v_cmp_gt_u32_e32 vcc, s13, v6
	s_and_saveexec_b64 s[6:7], vcc
	v_add_u32_e32 v160, 0x20000, v6
	v_lshrrev_b32_e32 v161, 5, v160
	v_mul_hi_u32 v161, v161, s12
	v_mul_u32_u24_e32 v162, 0x5a0, v161
	v_sub_u32_e32 v162, v160, v162
	v_mul_u32_u24_e32 v163, 0xb400, v161
	v_lshl_add_u32 v163, v162, 2, v163
	v_lshlrev_b32_e32 v164, 5, v161
	v_lshlrev_b32_e32 v165, 4, v161
	v_lshl_or_b32 v165, v162, 11, v165
	v_add_u32_e32 v166, 0x1680, v163
	v_add_u32_e32 v167, 0x2d00, v163
	v_add_u32_e32 v168, 0x4380, v163
	v_add_u32_e32 v169, 0x5a00, v163
	v_add_u32_e32 v170, 0x7080, v163
	v_add_u32_e32 v171, 0x8700, v163
	v_add_u32_e32 v172, 0x9d80, v163
	global_load_dword v226, v163, s[66:67]
	global_load_dword v227, v166, s[66:67]
	global_load_dword v228, v167, s[66:67]
	global_load_dword v229, v168, s[66:67]
	global_load_dword v230, v169, s[66:67]
	global_load_dword v231, v170, s[66:67]
	global_load_dword v232, v171, s[66:67]
	global_load_dword v233, v172, s[66:67]
	global_load_dwordx4 v[234:237], v164, s[64:65]
	global_load_dwordx4 v[238:241], v164, s[64:65] offset:16
	s_mov_b64 exec, s[6:7]
	s_waitcnt vmcnt(10)
	v_pk_mul_f32 v[210:211], v[210:211], v[218:219]
	v_pk_mul_f32 v[212:213], v[212:213], v[220:221]
	v_pk_mul_f32 v[214:215], v[214:215], v[222:223]
	v_pk_mul_f32 v[216:217], v[216:217], v[224:225]
	v_cvt_pk_bf16_f32 v242, v210, v211
	v_cvt_pk_bf16_f32 v243, v212, v213
	v_cvt_pk_bf16_f32 v244, v214, v215
	v_cvt_pk_bf16_f32 v245, v216, v217
	global_store_dwordx4 v205, v[242:245], s[80:81]
	s_nop 0
	v_cmp_gt_u32_e32 vcc, s13, v6
	s_and_saveexec_b64 s[6:7], vcc
	s_waitcnt vmcnt(1)
	v_pk_mul_f32 v[226:227], v[226:227], v[234:235]
	v_pk_mul_f32 v[228:229], v[228:229], v[236:237]
	v_pk_mul_f32 v[230:231], v[230:231], v[238:239]
	v_pk_mul_f32 v[232:233], v[232:233], v[240:241]
	v_cvt_pk_bf16_f32 v242, v226, v227
	v_cvt_pk_bf16_f32 v243, v228, v229
	v_cvt_pk_bf16_f32 v244, v230, v231
	v_cvt_pk_bf16_f32 v245, v232, v233
	global_store_dwordx4 v165, v[242:245], s[80:81]
	s_mov_b64 exec, s[6:7]

; DEVI uint32_t pk(float a, float b) { const hwf32x2 v = {a, b}; return __builtin_bit_cast(uint32_t, __builtin_convertvector(v, hwbf16x2)); }
; __device__ void phase_prep(const P& p, int vb, int nvb) {
;     ...
;     uint16_t* o = (uint16_t*)(ws + WS_WT_OUT); const float* w = p.in[14]; const float* ga = p.in[12]; const float* gc = p.in[13];
;     for (size_t i = gid; i < (size_t)512 * 1024; i += gsz) {
;       const int k = 2 * (int)(i >> 10), n = (int)(i & 1023);
;       const float g0 = k < 512 ? ga[k] : gc[k - 512], g1 = k < 512 ? ga[k + 1] : gc[k + 1 - 512];
;       *(uint32_t*)(o + (size_t)n * 1024 + k) = pk(w[(size_t)k * 1024 + n] * g0, w[(size_t)(k + 1) * 1024 + n] * g1);
;     }
;   }
;   {
;     uint16_t* o = (uint16_t*)(ws + WS_WT_PQ); const float* w = p.in[16]; const float* g = p.in[15];
;     for (size_t i = gid; i < (size_t)512 * 1024; i += gsz) {
;       const int k = 2 * (int)(i >> 10), n = (int)(i & 1023);
;       *(uint32_t*)(o + (size_t)n * 1024 + k) = pk(w[(size_t)k * 1024 + n] * g[k], w[(size_t)(k + 1) * 1024 + n] * g[k + 1]);
;     }
;   }
.LBB0_21:
	v_writelane_b32 v248, s18, 4
	s_nop 1
	v_writelane_b32 v248, s19, 5
	v_writelane_b32 v248, s16, 6
	s_nop 1
	v_writelane_b32 v248, s17, 7
	s_or_b64 exec, exec, s[0:1]
	s_add_u32 s22, s80, 0x3a0000
	s_addc_u32 s23, s81, 0
	s_waitcnt lgkmcnt(0)
	s_add_u32 s64, s80, 0x5a0000
	s_mov_b64 s[0:1], 0x80000
	s_addc_u32 s65, s81, 0
	v_cmp_gt_u64_e32 vcc, s[0:1], v[6:7]
	s_and_saveexec_b64 s[0:1], vcc
	s_cbranch_execz .LBB0_26
	v_and_b32_e32 v200, 0x3ff, v6
	v_lshrrev_b32_e32 v201, 10, v6
	v_lshlrev_b32_e32 v202, 2, v200
	v_lshl_add_u32 v204, v201, 15, v202
	v_lshlrev_b32_e32 v203, 5, v201
	v_lshlrev_b32_e32 v207, 4, v201
	v_lshl_or_b32 v207, v200, 11, v207
	v_add_u32_e32 v191, 0x1000, v204
	v_add_u32_e32 v192, 0x2000, v204
	v_add_u32_e32 v193, 0x3000, v204
	v_add_u32_e32 v194, 0x4000, v204
	v_add_u32_e32 v195, 0x5000, v204
	v_add_u32_e32 v196, 0x6000, v204
	v_add_u32_e32 v197, 0x7000, v204
	v_and_b32_e32 v198, 63, v201
	v_lshlrev_b32_e32 v198, 5, v198
	v_mov_b32_e32 v199, 0
	v_cmp_gt_u32_e32 vcc, 64, v201
	v_mov_b32_e32 v208, s54
	v_mov_b32_e32 v209, s55
	v_mov_b32_e32 v206, s52
	v_mov_b32_e32 v205, s53
	s_nop 0
	v_cndmask_b32_e32 v208, v208, v206, vcc
	v_cndmask_b32_e32 v209, v209, v205, vcc
	v_lshl_add_u64 v[208:209], v[208:209], 0, v[198:199]
	global_load_dword v210, v204, s[56:57]
	global_load_dword v211, v191, s[56:57]
	global_load_dword v212, v192, s[56:57]
	global_load_dword v213, v193, s[56:57]
	global_load_dword v214, v194, s[56:57]
	global_load_dword v215, v195, s[56:57]
	global_load_dword v216, v196, s[56:57]
	global_load_dword v217, v197, s[56:57]
	global_load_dwordx4 v[218:221], v[208:209], off
	global_load_dwordx4 v[222:225], v[208:209], off offset:16
	global_load_dword v226, v204, s[84:85]
	global_load_dword v227, v191, s[84:85]
	global_load_dword v228, v192, s[84:85]
	global_load_dword v229, v193, s[84:85]
	global_load_dword v230, v194, s[84:85]
	global_load_dword v231, v195, s[84:85]
	global_load_dword v232, v196, s[84:85]
	global_load_dword v233, v197, s[84:85]
	global_load_dwordx4 v[234:237], v203, s[58:59]
	global_load_dwordx4 v[238:241], v203, s[58:59] offset:16
	s_waitcnt vmcnt(10)
	v_pk_mul_f32 v[210:211], v[210:211], v[218:219]
	v_pk_mul_f32 v[212:213], v[212:213], v[220:221]
	v_pk_mul_f32 v[214:215], v[214:215], v[222:223]
	v_pk_mul_f32 v[216:217], v[216:217], v[224:225]
	v_cvt_pk_bf16_f32 v242, v210, v211
	v_cvt_pk_bf16_f32 v243, v212, v213
	v_cvt_pk_bf16_f32 v244, v214, v215
	v_cvt_pk_bf16_f32 v245, v216, v217
	global_store_dwordx4 v207, v[242:245], s[22:23]
	s_nop 0
	s_waitcnt vmcnt(1)
	v_pk_mul_f32 v[226:227], v[226:227], v[234:235]
	v_pk_mul_f32 v[228:229], v[228:229], v[236:237]
	v_pk_mul_f32 v[230:231], v[230:231], v[238:239]
	v_pk_mul_f32 v[232:233], v[232:233], v[240:241]
	v_cvt_pk_bf16_f32 v242, v226, v227
	v_cvt_pk_bf16_f32 v243, v228, v229
	v_cvt_pk_bf16_f32 v244, v230, v231
	v_cvt_pk_bf16_f32 v245, v232, v233
	global_store_dwordx4 v207, v[242:245], s[64:65]
